# weight conversion rounds: 8 tile-half loads + scale loads issued into private registers, single wait, multiplies deferred (phase 0 and per-layer FFN conversion)
# baseline (speedup 1.0000x reference)
; __device__ __forceinline__ void run_job(LAS float* tl, const Job j, int& tile_base) {
;     ...
;     for (int t0 = start; t0 < total; t0 += 4 * G) {
;         f32x4 v[4][2];
; #pragma unroll
;         for (int u = 0; u < 4; ++u) { const int t = t0 + u * G;
; #pragma unroll
;             for (int hh = 0; hh < 2; ++hh) { v[u][hh] = (f32x4){0.f, 0.f, 0.f, 0.f};
;                 if (t < total) { const int bi = t / per, r = t % per, tc = r / tk_n, tk = r % tk_n; const int idx = tid + 512 * hh, kk = idx >> 4, cc = (idx & 15) * 4, k = tk * 64 + kk, c = tc * 64 + cc;
;                     if (j.in != nullptr && k < j.K && c < j.ncols) { v[u][hh] = *(const f32x4*)(j.in + bi * j.ibs + (size_t)k * j.ld_in + c) * j.mul; if (j.scale) v[u][hh] *= j.scale[k]; } } } }
.LBB0_709:
	v_mov_b32_e32 v64, 0
	v_mov_b32_e32 v65, 0
	v_mov_b32_e32 v66, 0
	v_mov_b32_e32 v67, 0
	v_mov_b32_e32 v68, 0
	v_mov_b32_e32 v69, 0
	v_mov_b32_e32 v70, 0
	v_mov_b32_e32 v71, 0
	v_mov_b32_e32 v72, 0
	v_mov_b32_e32 v73, 0
	v_mov_b32_e32 v74, 0
	v_mov_b32_e32 v75, 0
	v_mov_b32_e32 v76, 0
	v_mov_b32_e32 v77, 0
	v_mov_b32_e32 v78, 0
	v_mov_b32_e32 v79, 0
	v_mov_b32_e32 v80, 0
	v_mov_b32_e32 v81, 0
	v_mov_b32_e32 v82, 0
	v_mov_b32_e32 v83, 0
	v_mov_b32_e32 v84, 0
	v_mov_b32_e32 v85, 0
	v_mov_b32_e32 v86, 0
	v_mov_b32_e32 v87, 0
	v_mov_b32_e32 v88, 0
	v_mov_b32_e32 v89, 0
	v_mov_b32_e32 v90, 0
	v_mov_b32_e32 v91, 0
	v_mov_b32_e32 v92, 0
	v_mov_b32_e32 v93, 0
	v_mov_b32_e32 v94, 0
	v_mov_b32_e32 v95, 0
	v_mov_b32_e32 v96, 1.0
	v_mov_b32_e32 v98, 1.0
	v_mov_b32_e32 v100, 1.0
	v_mov_b32_e32 v102, 1.0
	v_mov_b32_e32 v104, 1.0
	v_mov_b32_e32 v106, 1.0
	v_mov_b32_e32 v108, 1.0
	v_mov_b32_e32 v110, 1.0
	s_abs_i32 s5, s69
	s_mul_hi_u32 s6, s5, s72
	s_mul_i32 s7, s6, s68
	s_sub_i32 s5, s5, s7
	s_ashr_i32 s4, s69, 31
	s_add_i32 s7, s6, 1
	s_sub_i32 s8, s5, s68
	s_cmp_ge_u32 s5, s68
	s_cselect_b32 s6, s7, s6
	s_cselect_b32 s5, s8, s5
	s_add_i32 s7, s6, 1
	s_cmp_ge_u32 s5, s68
	s_cselect_b32 s5, s7, s6
	s_xor_b32 s5, s5, s4
	s_sub_i32 s60, s5, s4
	s_mul_i32 s4, s60, s68
	s_sub_i32 s4, s69, s4
	s_abs_i32 s6, s4
	s_mul_hi_u32 s7, s6, s73
	s_mul_i32 s8, s7, s67
	s_sub_i32 s6, s6, s8
	s_ashr_i32 s5, s4, 31
	s_add_i32 s8, s7, 1
	s_sub_i32 s9, s6, s67
	s_cmp_ge_u32 s6, s67
	s_cselect_b32 s7, s8, s7
	s_cselect_b32 s6, s9, s6
	s_add_i32 s8, s7, 1
	s_cmp_ge_u32 s6, s67
	s_cselect_b32 s6, s8, s7
	s_xor_b32 s6, s6, s5
	s_sub_i32 s5, s6, s5
	s_mul_i32 s6, s5, s67
	s_sub_i32 s4, s4, s6
	s_lshl_b32 s74, s4, 6
	v_add_u32_e32 v8, s74, v39
	s_lshl_b32 s75, s5, 6
	v_or_b32_e32 v10, s75, v38
	v_cmp_gt_i32_e32 vcc, s65, v8
	s_and_b64 s[4:5], s[50:51], vcc
	v_cmp_gt_i32_e64 s[42:43], s66, v10
	s_and_b64 s[4:5], s[4:5], s[42:43]
	v_mov_b32_e32 v2, 0
	v_ashrrev_i32_e32 v11, 31, v10
	s_mul_hi_i32 s45, s23, s60
	s_mul_i32 s44, s23, s60
	v_mov_b32_e32 v6, 0
	v_mov_b32_e32 v7, 0
	v_mov_b32_e32 v4, 0
	v_mov_b32_e32 v5, 0
	s_and_saveexec_b64 s[46:47], s[4:5]
	s_cbranch_execz .LBB0_712
	s_lshl_b64 s[4:5], s[44:45], 2
	s_add_u32 s4, s70, s4
	s_addc_u32 s5, s71, s5
	v_mad_i64_i32 v[4:5], s[6:7], s24, v8, 0
	v_lshl_add_u64 v[4:5], v[4:5], 2, s[4:5]
	v_lshl_add_u64 v[4:5], v[10:11], 2, v[4:5]
	global_load_dwordx4 v[64:67], v[4:5], off
	s_andn2_b64 vcc, exec, s[54:55]
	s_cbranch_vccnz .LBB0_712
	v_ashrrev_i32_e32 v9, 31, v8
	v_lshl_add_u64 v[8:9], v[8:9], 2, s[38:39]
	global_load_dword v96, v[8:9], off
.LBB0_712:
	s_or_b64 exec, exec, s[46:47]
	v_add_u32_e32 v12, s74, v40
	v_cmp_gt_i32_e32 vcc, s65, v12
	s_and_b64 s[4:5], s[50:51], vcc
	s_and_b64 s[4:5], s[4:5], s[42:43]
	v_mov_b32_e32 v3, 0
	v_mov_b32_e32 v8, 0
	v_mov_b32_e32 v9, 0
	s_and_saveexec_b64 s[42:43], s[4:5]
	s_cbranch_execz .LBB0_715
	s_lshl_b64 s[4:5], s[44:45], 2
	s_add_u32 s4, s70, s4
	s_addc_u32 s5, s71, s5
	v_mad_i64_i32 v[2:3], s[6:7], s24, v12, 0
	v_lshl_add_u64 v[2:3], v[2:3], 2, s[4:5]
	v_lshl_add_u64 v[2:3], v[10:11], 2, v[2:3]
	global_load_dwordx4 v[68:71], v[2:3], off
	s_andn2_b64 vcc, exec, s[54:55]
	s_cbranch_vccnz .LBB0_715
	v_ashrrev_i32_e32 v13, 31, v12
	v_lshl_add_u64 v[10:11], v[12:13], 2, s[38:39]
	global_load_dword v98, v[10:11], off
.LBB0_715:
	s_or_b64 exec, exec, s[42:43]
	s_add_i32 s4, s69, s96
	s_cmp_lt_i32 s4, s25
	v_mov_b32_e32 v10, 0
	s_cselect_b64 s[44:45], -1, 0
	s_cmp_ge_i32 s4, s25
	v_mov_b32_e32 v14, 0
	v_mov_b32_e32 v15, 0
	v_mov_b32_e32 v12, 0
	v_mov_b32_e32 v13, 0
	s_cbranch_scc1 .LBB0_720
	s_abs_i32 s7, s4
	s_mul_hi_u32 s6, s7, s72
	s_mul_i32 s8, s6, s68
	s_sub_i32 s7, s7, s8
	s_ashr_i32 s5, s4, 31
	s_sub_i32 s10, s7, s68
	s_cmp_ge_u32 s7, s68
	s_cselect_b64 s[46:47], -1, 0
	s_and_b64 s[8:9], s[46:47], exec
	s_cselect_b32 s7, s10, s7
	s_sub_i32 s10, s7, s68
	s_cmp_ge_u32 s7, s68
	s_cselect_b64 s[48:49], -1, 0
	s_and_b64 s[8:9], s[48:49], exec
	s_cselect_b32 s7, s10, s7
	s_xor_b32 s7, s7, s5
	s_sub_i32 s7, s7, s5
	s_abs_i32 s9, s7
	s_mul_hi_u32 s10, s9, s73
	s_mul_i32 s11, s10, s67
	s_sub_i32 s9, s9, s11
	s_ashr_i32 s8, s7, 31
	s_add_i32 s11, s10, 1
	s_sub_i32 s12, s9, s67
	s_cmp_ge_u32 s9, s67
	s_cselect_b32 s10, s11, s10
	s_cselect_b32 s9, s12, s9
	s_add_i32 s11, s10, 1
	s_cmp_ge_u32 s9, s67
	s_cselect_b32 s9, s11, s10
	s_xor_b32 s9, s9, s8
	s_sub_i32 s8, s9, s8
	s_mul_i32 s9, s8, s67
	s_sub_i32 s7, s7, s9
	v_lshl_add_u32 v16, s7, 6, v39
	v_lshl_or_b32 v18, s8, 6, v38
	v_cmp_gt_i32_e32 vcc, s65, v16
	s_and_b64 s[8:9], s[50:51], vcc
	v_cmp_gt_i32_e32 vcc, s66, v18
	s_and_b64 s[8:9], s[8:9], vcc
	v_mov_b32_e32 v13, 0
	v_mov_b32_e32 v12, 0
	v_mov_b32_e32 v15, 0
	v_mov_b32_e32 v14, 0
	s_and_saveexec_b64 s[42:43], s[8:9]
	s_cbranch_execz .LBB0_719
	s_add_i32 s7, s6, 1
	s_and_b64 s[8:9], s[46:47], exec
	s_cselect_b32 s8, s7, s6
	s_add_i32 s9, s8, 1
	s_and_b64 s[6:7], s[48:49], exec
	s_cselect_b32 s6, s9, s8
	s_xor_b32 s6, s6, s5
	s_sub_i32 s5, s6, s5
	s_mul_hi_i32 s7, s23, s5
	s_mul_i32 s6, s23, s5
	s_lshl_b64 s[6:7], s[6:7], 2
	s_add_u32 s6, s70, s6
	s_addc_u32 s7, s71, s7
	v_mad_i64_i32 v[12:13], s[8:9], s24, v16, 0
	v_lshl_add_u64 v[12:13], v[12:13], 2, s[6:7]
	v_ashrrev_i32_e32 v19, 31, v18
	v_lshl_add_u64 v[12:13], v[18:19], 2, v[12:13]
	global_load_dwordx4 v[72:75], v[12:13], off
	s_andn2_b64 vcc, exec, s[54:55]
	s_cbranch_vccnz .LBB0_719
	v_ashrrev_i32_e32 v17, 31, v16
	v_lshl_add_u64 v[16:17], v[16:17], 2, s[38:39]
	global_load_dword v100, v[16:17], off

; __device__ __forceinline__ void run_job(LAS float* tl, const Job j, int& tile_base) {
;     ...
;         for (int u = 0; u < 4; ++u) { const int t = t0 + u * G;
; #pragma unroll
;             for (int hh = 0; hh < 2; ++hh) { v[u][hh] = (f32x4){0.f, 0.f, 0.f, 0.f};
;                 if (t < total) { const int bi = t / per, r = t % per, tc = r / tk_n, tk = r % tk_n; const int idx = tid + 512 * hh, kk = idx >> 4, cc = (idx & 15) * 4, k = tk * 64 + kk, c = tc * 64 + cc;
;                     if (j.in != nullptr && k < j.K && c < j.ncols) { v[u][hh] = *(const f32x4*)(j.in + bi * j.ibs + (size_t)k * j.ld_in + c) * j.mul; if (j.scale) v[u][hh] *= j.scale[k]; } } } }
.LBB0_720:
	v_cndmask_b32_e64 v11, 0, 1, s[44:45]
	v_cmp_ne_u32_e64 s[42:43], 1, v11
	s_andn2_b64 vcc, exec, s[44:45]
	v_mov_b32_e32 v11, 0
	v_mov_b32_e32 v16, 0
	v_mov_b32_e32 v17, 0
	s_cbranch_vccnz .LBB0_725
	s_abs_i32 s7, s4
	s_mul_hi_u32 s6, s7, s72
	s_mul_i32 s8, s6, s68
	s_sub_i32 s7, s7, s8
	s_ashr_i32 s5, s4, 31
	s_sub_i32 s10, s7, s68
	s_cmp_ge_u32 s7, s68
	s_cselect_b64 s[46:47], -1, 0
	s_and_b64 s[8:9], s[46:47], exec
	s_cselect_b32 s7, s10, s7
	s_sub_i32 s10, s7, s68
	s_cmp_ge_u32 s7, s68
	s_cselect_b64 s[48:49], -1, 0
	s_and_b64 s[8:9], s[48:49], exec
	s_cselect_b32 s7, s10, s7
	s_xor_b32 s7, s7, s5
	s_sub_i32 s7, s7, s5
	s_abs_i32 s9, s7
	s_mul_hi_u32 s10, s9, s73
	s_mul_i32 s11, s10, s67
	s_sub_i32 s9, s9, s11
	s_ashr_i32 s8, s7, 31
	s_add_i32 s11, s10, 1
	s_sub_i32 s12, s9, s67
	s_cmp_ge_u32 s9, s67
	s_cselect_b32 s10, s11, s10
	s_cselect_b32 s9, s12, s9
	s_add_i32 s11, s10, 1
	s_cmp_ge_u32 s9, s67
	s_cselect_b32 s9, s11, s10
	s_xor_b32 s9, s9, s8
	s_sub_i32 s8, s9, s8
	s_mul_i32 s9, s8, s67
	s_sub_i32 s7, s7, s9
	v_lshl_add_u32 v18, s7, 6, v40
	v_lshl_or_b32 v20, s8, 6, v38
	v_cmp_gt_i32_e32 vcc, s65, v18
	s_and_b64 s[8:9], s[50:51], vcc
	v_cmp_gt_i32_e32 vcc, s66, v20
	s_and_b64 s[8:9], s[8:9], vcc
	v_mov_b32_e32 v17, 0
	v_mov_b32_e32 v16, 0
	v_mov_b32_e32 v11, 0
	v_mov_b32_e32 v10, 0
	s_and_saveexec_b64 s[44:45], s[8:9]
	s_cbranch_execz .LBB0_724
	s_add_i32 s7, s6, 1
	s_and_b64 s[8:9], s[46:47], exec
	s_cselect_b32 s8, s7, s6
	s_add_i32 s9, s8, 1
	s_and_b64 s[6:7], s[48:49], exec
	s_cselect_b32 s6, s9, s8
	s_xor_b32 s6, s6, s5
	s_sub_i32 s5, s6, s5
	s_mul_hi_i32 s7, s23, s5
	s_mul_i32 s6, s23, s5
	s_lshl_b64 s[6:7], s[6:7], 2
	s_add_u32 s6, s70, s6
	s_addc_u32 s7, s71, s7
	v_mad_i64_i32 v[10:11], s[8:9], s24, v18, 0
	v_lshl_add_u64 v[10:11], v[10:11], 2, s[6:7]
	v_ashrrev_i32_e32 v21, 31, v20
	v_lshl_add_u64 v[10:11], v[20:21], 2, v[10:11]
	global_load_dwordx4 v[76:79], v[10:11], off
	s_andn2_b64 vcc, exec, s[54:55]
	s_cbranch_vccnz .LBB0_724
	v_ashrrev_i32_e32 v19, 31, v18
	v_lshl_add_u64 v[18:19], v[18:19], 2, s[38:39]
	global_load_dword v102, v[18:19], off

; __device__ __forceinline__ void run_job(LAS float* tl, const Job j, int& tile_base) {
;     ...
;         for (int u = 0; u < 4; ++u) { const int t = t0 + u * G;
; #pragma unroll
;             for (int hh = 0; hh < 2; ++hh) { v[u][hh] = (f32x4){0.f, 0.f, 0.f, 0.f};
;                 if (t < total) { const int bi = t / per, r = t % per, tc = r / tk_n, tk = r % tk_n; const int idx = tid + 512 * hh, kk = idx >> 4, cc = (idx & 15) * 4, k = tk * 64 + kk, c = tc * 64 + cc;
;                     if (j.in != nullptr && k < j.K && c < j.ncols) { v[u][hh] = *(const f32x4*)(j.in + bi * j.ibs + (size_t)k * j.ld_in + c) * j.mul; if (j.scale) v[u][hh] *= j.scale[k]; } } } }
.LBB0_725:
	s_add_i32 s5, s4, s96
	s_cmp_lt_i32 s5, s25
	v_mov_b32_e32 v18, 0
	s_cselect_b64 s[46:47], -1, 0
	s_cmp_ge_i32 s5, s25
	v_mov_b32_e32 v22, 0
	v_mov_b32_e32 v23, 0
	v_mov_b32_e32 v20, 0
	v_mov_b32_e32 v21, 0
	s_cbranch_scc1 .LBB0_730
	s_abs_i32 s8, s5
	s_mul_hi_u32 s7, s8, s72
	s_mul_i32 s9, s7, s68
	s_sub_i32 s10, s8, s9
	s_ashr_i32 s6, s5, 31
	s_sub_i32 s11, s10, s68
	s_cmp_ge_u32 s10, s68
	s_cselect_b64 s[48:49], -1, 0
	s_and_b64 s[8:9], s[48:49], exec
	s_cselect_b32 s10, s11, s10
	s_sub_i32 s11, s10, s68
	s_cmp_ge_u32 s10, s68
	s_cselect_b64 s[56:57], -1, 0
	s_and_b64 s[8:9], s[56:57], exec
	s_cselect_b32 s8, s11, s10
	s_xor_b32 s8, s8, s6
	s_sub_i32 s8, s8, s6
	s_abs_i32 s10, s8
	s_mul_hi_u32 s11, s10, s73
	s_mul_i32 s12, s11, s67
	s_sub_i32 s10, s10, s12
	s_ashr_i32 s9, s8, 31
	s_add_i32 s12, s11, 1
	s_sub_i32 s13, s10, s67
	s_cmp_ge_u32 s10, s67
	s_cselect_b32 s11, s12, s11
	s_cselect_b32 s10, s13, s10
	s_add_i32 s12, s11, 1
	s_cmp_ge_u32 s10, s67
	s_cselect_b32 s10, s12, s11
	s_xor_b32 s10, s10, s9
	s_sub_i32 s9, s10, s9
	s_mul_i32 s10, s9, s67
	s_sub_i32 s8, s8, s10
	v_lshl_add_u32 v24, s8, 6, v39
	v_lshl_or_b32 v26, s9, 6, v38
	v_cmp_gt_i32_e32 vcc, s65, v24
	s_and_b64 s[8:9], s[50:51], vcc
	v_cmp_gt_i32_e32 vcc, s66, v26
	s_and_b64 s[8:9], s[8:9], vcc
	v_mov_b32_e32 v21, 0
	v_mov_b32_e32 v20, 0
	v_mov_b32_e32 v23, 0
	v_mov_b32_e32 v22, 0
	s_and_saveexec_b64 s[44:45], s[8:9]
	s_cbranch_execz .LBB0_729
	s_add_i32 s10, s7, 1
	s_and_b64 s[8:9], s[48:49], exec
	s_cselect_b32 s7, s10, s7
	s_add_i32 s10, s7, 1
	s_and_b64 s[8:9], s[56:57], exec
	s_cselect_b32 s7, s10, s7
	s_xor_b32 s7, s7, s6
	s_sub_i32 s6, s7, s6
	s_mul_hi_i32 s7, s23, s6
	s_mul_i32 s6, s23, s6
	s_lshl_b64 s[6:7], s[6:7], 2
	s_add_u32 s6, s70, s6
	s_addc_u32 s7, s71, s7
	v_mad_i64_i32 v[20:21], s[8:9], s24, v24, 0
	v_lshl_add_u64 v[20:21], v[20:21], 2, s[6:7]
	v_ashrrev_i32_e32 v27, 31, v26
	v_lshl_add_u64 v[20:21], v[26:27], 2, v[20:21]
	global_load_dwordx4 v[80:83], v[20:21], off
	s_andn2_b64 vcc, exec, s[54:55]
	s_cbranch_vccnz .LBB0_729
	v_ashrrev_i32_e32 v25, 31, v24
	v_lshl_add_u64 v[24:25], v[24:25], 2, s[38:39]
	global_load_dword v104, v[24:25], off

; __device__ __forceinline__ void run_job(LAS float* tl, const Job j, int& tile_base) {
;     ...
;         for (int u = 0; u < 4; ++u) { const int t = t0 + u * G;
; #pragma unroll
;             for (int hh = 0; hh < 2; ++hh) { v[u][hh] = (f32x4){0.f, 0.f, 0.f, 0.f};
;                 if (t < total) { const int bi = t / per, r = t % per, tc = r / tk_n, tk = r % tk_n; const int idx = tid + 512 * hh, kk = idx >> 4, cc = (idx & 15) * 4, k = tk * 64 + kk, c = tc * 64 + cc;
;                     if (j.in != nullptr && k < j.K && c < j.ncols) { v[u][hh] = *(const f32x4*)(j.in + bi * j.ibs + (size_t)k * j.ld_in + c) * j.mul; if (j.scale) v[u][hh] *= j.scale[k]; } } } }
.LBB0_730:
	v_cndmask_b32_e64 v19, 0, 1, s[46:47]
	v_cmp_ne_u32_e64 s[44:45], 1, v19
	s_andn2_b64 vcc, exec, s[46:47]
	v_mov_b32_e32 v19, 0
	v_mov_b32_e32 v24, 0
	v_mov_b32_e32 v25, 0
	s_cbranch_vccnz .LBB0_735
	s_abs_i32 s8, s5
	s_mul_hi_u32 s7, s8, s72
	s_mul_i32 s9, s7, s68
	s_sub_i32 s10, s8, s9
	s_ashr_i32 s6, s5, 31
	s_sub_i32 s11, s10, s68
	s_cmp_ge_u32 s10, s68
	s_cselect_b64 s[48:49], -1, 0
	s_and_b64 s[8:9], s[48:49], exec
	s_cselect_b32 s10, s11, s10
	s_sub_i32 s11, s10, s68
	s_cmp_ge_u32 s10, s68
	s_cselect_b64 s[56:57], -1, 0
	s_and_b64 s[8:9], s[56:57], exec
	s_cselect_b32 s8, s11, s10
	s_xor_b32 s8, s8, s6
	s_sub_i32 s8, s8, s6
	s_abs_i32 s10, s8
	s_mul_hi_u32 s11, s10, s73
	s_mul_i32 s12, s11, s67
	s_sub_i32 s10, s10, s12
	s_ashr_i32 s9, s8, 31
	s_add_i32 s12, s11, 1
	s_sub_i32 s13, s10, s67
	s_cmp_ge_u32 s10, s67
	s_cselect_b32 s11, s12, s11
	s_cselect_b32 s10, s13, s10
	s_add_i32 s12, s11, 1
	s_cmp_ge_u32 s10, s67
	s_cselect_b32 s10, s12, s11
	s_xor_b32 s10, s10, s9
	s_sub_i32 s9, s10, s9
	s_mul_i32 s10, s9, s67
	s_sub_i32 s8, s8, s10
	v_lshl_add_u32 v26, s8, 6, v40
	v_lshl_or_b32 v28, s9, 6, v38
	v_cmp_gt_i32_e32 vcc, s65, v26
	s_and_b64 s[8:9], s[50:51], vcc
	v_cmp_gt_i32_e32 vcc, s66, v28
	s_and_b64 s[8:9], s[8:9], vcc
	v_mov_b32_e32 v25, 0
	v_mov_b32_e32 v24, 0
	v_mov_b32_e32 v19, 0
	v_mov_b32_e32 v18, 0
	s_and_saveexec_b64 s[46:47], s[8:9]
	s_cbranch_execz .LBB0_734
	s_add_i32 s10, s7, 1
	s_and_b64 s[8:9], s[48:49], exec
	s_cselect_b32 s7, s10, s7
	s_add_i32 s10, s7, 1
	s_and_b64 s[8:9], s[56:57], exec
	s_cselect_b32 s7, s10, s7
	s_xor_b32 s7, s7, s6
	s_sub_i32 s6, s7, s6
	s_mul_hi_i32 s7, s23, s6
	s_mul_i32 s6, s23, s6
	s_lshl_b64 s[6:7], s[6:7], 2
	s_add_u32 s6, s70, s6
	s_addc_u32 s7, s71, s7
	v_mad_i64_i32 v[18:19], s[8:9], s24, v26, 0
	v_lshl_add_u64 v[18:19], v[18:19], 2, s[6:7]
	v_ashrrev_i32_e32 v29, 31, v28
	v_lshl_add_u64 v[18:19], v[28:29], 2, v[18:19]
	global_load_dwordx4 v[84:87], v[18:19], off
	s_andn2_b64 vcc, exec, s[54:55]
	s_cbranch_vccnz .LBB0_734
	v_ashrrev_i32_e32 v27, 31, v26
	v_lshl_add_u64 v[26:27], v[26:27], 2, s[38:39]
	global_load_dword v106, v[26:27], off

; __device__ __forceinline__ void run_job(LAS float* tl, const Job j, int& tile_base) {
;     ...
;         for (int u = 0; u < 4; ++u) { const int t = t0 + u * G;
; #pragma unroll
;             for (int hh = 0; hh < 2; ++hh) { v[u][hh] = (f32x4){0.f, 0.f, 0.f, 0.f};
;                 if (t < total) { const int bi = t / per, r = t % per, tc = r / tk_n, tk = r % tk_n; const int idx = tid + 512 * hh, kk = idx >> 4, cc = (idx & 15) * 4, k = tk * 64 + kk, c = tc * 64 + cc;
;                     if (j.in != nullptr && k < j.K && c < j.ncols) { v[u][hh] = *(const f32x4*)(j.in + bi * j.ibs + (size_t)k * j.ld_in + c) * j.mul; if (j.scale) v[u][hh] *= j.scale[k]; } } } }
.LBB0_735:
	s_add_i32 s6, s5, s96
	s_cmp_lt_i32 s6, s25
	v_mov_b32_e32 v26, 0
	s_cselect_b64 s[48:49], -1, 0
	s_cmp_ge_i32 s6, s25
	v_mov_b32_e32 v30, 0
	v_mov_b32_e32 v31, 0
	v_mov_b32_e32 v28, 0
	v_mov_b32_e32 v29, 0
	s_cbranch_scc1 .LBB0_740
	s_abs_i32 s9, s6
	s_mul_hi_u32 s8, s9, s72
	s_mul_i32 s10, s8, s68
	s_sub_i32 s9, s9, s10
	s_ashr_i32 s7, s6, 31
	s_sub_i32 s12, s9, s68
	s_cmp_ge_u32 s9, s68
	s_cselect_b64 s[56:57], -1, 0
	s_and_b64 s[10:11], s[56:57], exec
	s_cselect_b32 s9, s12, s9
	s_sub_i32 s12, s9, s68
	s_cmp_ge_u32 s9, s68
	s_cselect_b64 s[58:59], -1, 0
	s_and_b64 s[10:11], s[58:59], exec
	s_cselect_b32 s9, s12, s9
	s_xor_b32 s9, s9, s7
	s_sub_i32 s9, s9, s7
	s_abs_i32 s11, s9
	s_mul_hi_u32 s12, s11, s73
	s_mul_i32 s13, s12, s67
	s_sub_i32 s11, s11, s13
	s_ashr_i32 s10, s9, 31
	s_add_i32 s13, s12, 1
	s_sub_i32 s14, s11, s67
	s_cmp_ge_u32 s11, s67
	s_cselect_b32 s12, s13, s12
	s_cselect_b32 s11, s14, s11
	s_add_i32 s13, s12, 1
	s_cmp_ge_u32 s11, s67
	s_cselect_b32 s11, s13, s12
	s_xor_b32 s11, s11, s10
	s_sub_i32 s10, s11, s10
	s_mul_i32 s11, s10, s67
	s_sub_i32 s9, s9, s11
	v_lshl_add_u32 v32, s9, 6, v39
	v_lshl_or_b32 v34, s10, 6, v38
	v_cmp_gt_i32_e32 vcc, s65, v32
	s_and_b64 s[10:11], s[50:51], vcc
	v_cmp_gt_i32_e32 vcc, s66, v34
	s_and_b64 s[10:11], s[10:11], vcc
	v_mov_b32_e32 v29, 0
	v_mov_b32_e32 v28, 0
	v_mov_b32_e32 v31, 0
	v_mov_b32_e32 v30, 0
	s_and_saveexec_b64 s[46:47], s[10:11]
	s_cbranch_execz .LBB0_739
	s_add_i32 s9, s8, 1
	s_and_b64 s[10:11], s[56:57], exec
	s_cselect_b32 s10, s9, s8
	s_add_i32 s11, s10, 1
	s_and_b64 s[8:9], s[58:59], exec
	s_cselect_b32 s8, s11, s10
	s_xor_b32 s8, s8, s7
	s_sub_i32 s7, s8, s7
	s_mul_hi_i32 s9, s23, s7
	s_mul_i32 s8, s23, s7
	s_lshl_b64 s[8:9], s[8:9], 2
	s_add_u32 s8, s70, s8
	s_addc_u32 s9, s71, s9
	v_mad_i64_i32 v[28:29], s[10:11], s24, v32, 0
	v_lshl_add_u64 v[28:29], v[28:29], 2, s[8:9]
	v_ashrrev_i32_e32 v35, 31, v34
	v_lshl_add_u64 v[28:29], v[34:35], 2, v[28:29]
	global_load_dwordx4 v[88:91], v[28:29], off
	s_andn2_b64 vcc, exec, s[54:55]
	s_cbranch_vccnz .LBB0_739
	v_ashrrev_i32_e32 v33, 31, v32
	v_lshl_add_u64 v[32:33], v[32:33], 2, s[38:39]
	global_load_dword v108, v[32:33], off

; __device__ __forceinline__ void run_job(LAS float* tl, const Job j, int& tile_base) {
;     ...
;         for (int u = 0; u < 4; ++u) { const int t = t0 + u * G;
; #pragma unroll
;             for (int hh = 0; hh < 2; ++hh) { v[u][hh] = (f32x4){0.f, 0.f, 0.f, 0.f};
;                 if (t < total) { const int bi = t / per, r = t % per, tc = r / tk_n, tk = r % tk_n; const int idx = tid + 512 * hh, kk = idx >> 4, cc = (idx & 15) * 4, k = tk * 64 + kk, c = tc * 64 + cc;
;                     if (j.in != nullptr && k < j.K && c < j.ncols) { v[u][hh] = *(const f32x4*)(j.in + bi * j.ibs + (size_t)k * j.ld_in + c) * j.mul; if (j.scale) v[u][hh] *= j.scale[k]; } } } }
.LBB0_740:
	v_cndmask_b32_e64 v27, 0, 1, s[48:49]
	v_cmp_ne_u32_e64 s[46:47], 1, v27
	s_andn2_b64 vcc, exec, s[48:49]
	v_mov_b32_e32 v27, 0
	v_mov_b32_e32 v32, 0
	v_mov_b32_e32 v33, 0
	s_cbranch_vccnz .LBB0_745
	s_abs_i32 s9, s6
	s_mul_hi_u32 s8, s9, s72
	s_mul_i32 s10, s8, s68
	s_sub_i32 s9, s9, s10
	s_ashr_i32 s7, s6, 31
	s_sub_i32 s12, s9, s68
	s_cmp_ge_u32 s9, s68
	s_cselect_b64 s[56:57], -1, 0
	s_and_b64 s[10:11], s[56:57], exec
	s_cselect_b32 s9, s12, s9
	s_sub_i32 s12, s9, s68
	s_cmp_ge_u32 s9, s68
	s_cselect_b64 s[58:59], -1, 0
	s_and_b64 s[10:11], s[58:59], exec
	s_cselect_b32 s9, s12, s9
	s_xor_b32 s9, s9, s7
	s_sub_i32 s9, s9, s7
	s_abs_i32 s11, s9
	s_mul_hi_u32 s12, s11, s73
	s_mul_i32 s13, s12, s67
	s_sub_i32 s11, s11, s13
	s_ashr_i32 s10, s9, 31
	s_add_i32 s13, s12, 1
	s_sub_i32 s14, s11, s67
	s_cmp_ge_u32 s11, s67
	s_cselect_b32 s12, s13, s12
	s_cselect_b32 s11, s14, s11
	s_add_i32 s13, s12, 1
	s_cmp_ge_u32 s11, s67
	s_cselect_b32 s11, s13, s12
	s_xor_b32 s11, s11, s10
	s_sub_i32 s10, s11, s10
	s_mul_i32 s11, s10, s67
	s_sub_i32 s9, s9, s11
	v_lshl_add_u32 v34, s9, 6, v40
	v_lshl_or_b32 v36, s10, 6, v38
	v_cmp_gt_i32_e32 vcc, s65, v34
	s_and_b64 s[10:11], s[50:51], vcc
	v_cmp_gt_i32_e32 vcc, s66, v36
	s_and_b64 s[10:11], s[10:11], vcc
	v_mov_b32_e32 v33, 0
	v_mov_b32_e32 v32, 0
	v_mov_b32_e32 v27, 0
	v_mov_b32_e32 v26, 0
	s_and_saveexec_b64 s[48:49], s[10:11]
	s_cbranch_execz .LBB0_744
	s_add_i32 s9, s8, 1
	s_and_b64 s[10:11], s[56:57], exec
	s_cselect_b32 s10, s9, s8
	s_add_i32 s11, s10, 1
	s_and_b64 s[8:9], s[58:59], exec
	s_cselect_b32 s8, s11, s10
	s_xor_b32 s8, s8, s7
	s_sub_i32 s7, s8, s7
	s_mul_hi_i32 s9, s23, s7
	s_mul_i32 s8, s23, s7
	s_lshl_b64 s[8:9], s[8:9], 2
	s_add_u32 s8, s70, s8
	s_addc_u32 s9, s71, s9
	v_mad_i64_i32 v[26:27], s[10:11], s24, v34, 0
	v_lshl_add_u64 v[26:27], v[26:27], 2, s[8:9]
	v_ashrrev_i32_e32 v37, 31, v36
	v_lshl_add_u64 v[26:27], v[36:37], 2, v[26:27]
	global_load_dwordx4 v[92:95], v[26:27], off
	s_andn2_b64 vcc, exec, s[54:55]
	s_cbranch_vccnz .LBB0_744
	v_ashrrev_i32_e32 v35, 31, v34
	v_lshl_add_u64 v[34:35], v[34:35], 2, s[38:39]
	global_load_dword v110, v[34:35], off

; __device__ __forceinline__ void run_job(LAS float* tl, const Job j, int& tile_base) {
;     ...
;                     if (j.in != nullptr && k < j.K && c < j.ncols) { v[u][hh] = *(const f32x4*)(j.in + bi * j.ibs + (size_t)k * j.ld_in + c) * j.mul; if (j.scale) v[u][hh] *= j.scale[k]; } } } }
.LBB0_745:
	s_waitcnt vmcnt(0)
	v_pk_mul_f32 v[4:5], s[52:53], v[66:67]
	v_pk_mul_f32 v[6:7], s[0:1], v[64:65]
	v_pk_mul_f32 v[8:9], s[52:53], v[70:71]
	v_pk_mul_f32 v[2:3], s[0:1], v[68:69]
	v_pk_mul_f32 v[12:13], s[52:53], v[74:75]
	v_pk_mul_f32 v[14:15], s[0:1], v[72:73]
	v_pk_mul_f32 v[16:17], s[52:53], v[78:79]
	v_pk_mul_f32 v[10:11], s[0:1], v[76:77]
	v_pk_mul_f32 v[20:21], s[52:53], v[82:83]
	v_pk_mul_f32 v[22:23], s[0:1], v[80:81]
	v_pk_mul_f32 v[24:25], s[52:53], v[86:87]
	v_pk_mul_f32 v[18:19], s[0:1], v[84:85]
	v_pk_mul_f32 v[28:29], s[52:53], v[90:91]
	v_pk_mul_f32 v[30:31], s[0:1], v[88:89]
	v_pk_mul_f32 v[32:33], s[52:53], v[94:95]
	v_pk_mul_f32 v[26:27], s[0:1], v[92:93]
	s_andn2_b64 vcc, exec, s[54:55]
	s_cbranch_vccnz .Lcv_ffn_ns
	v_pk_mul_f32 v[4:5], v[4:5], v[96:97] op_sel_hi:[1,0]
	v_pk_mul_f32 v[6:7], v[6:7], v[96:97] op_sel_hi:[1,0]
	v_pk_mul_f32 v[8:9], v[8:9], v[98:99] op_sel_hi:[1,0]
	v_pk_mul_f32 v[2:3], v[2:3], v[98:99] op_sel_hi:[1,0]
	v_pk_mul_f32 v[12:13], v[12:13], v[100:101] op_sel_hi:[1,0]
	v_pk_mul_f32 v[14:15], v[14:15], v[100:101] op_sel_hi:[1,0]
	v_pk_mul_f32 v[16:17], v[16:17], v[102:103] op_sel_hi:[1,0]
	v_pk_mul_f32 v[10:11], v[10:11], v[102:103] op_sel_hi:[1,0]
	v_pk_mul_f32 v[20:21], v[20:21], v[104:105] op_sel_hi:[1,0]
	v_pk_mul_f32 v[22:23], v[22:23], v[104:105] op_sel_hi:[1,0]
	v_pk_mul_f32 v[24:25], v[24:25], v[106:107] op_sel_hi:[1,0]
	v_pk_mul_f32 v[18:19], v[18:19], v[106:107] op_sel_hi:[1,0]
	v_pk_mul_f32 v[28:29], v[28:29], v[108:109] op_sel_hi:[1,0]
	v_pk_mul_f32 v[30:31], v[30:31], v[108:109] op_sel_hi:[1,0]
	v_pk_mul_f32 v[32:33], v[32:33], v[110:111] op_sel_hi:[1,0]
	v_pk_mul_f32 v[26:27], v[26:27], v[110:111] op_sel_hi:[1,0]

; __device__ __forceinline__ void run_job(LAS float* tl, const Job j, int& tile_base) {
;     ...
;     for (int t0 = start; t0 < total; t0 += 4 * G) {
;         f32x4 v[4][2];
; #pragma unroll
;         for (int u = 0; u < 4; ++u) { const int t = t0 + u * G;
; #pragma unroll
;             for (int hh = 0; hh < 2; ++hh) { v[u][hh] = (f32x4){0.f, 0.f, 0.f, 0.f};
;                 if (t < total) { const int bi = t / per, r = t % per, tc = r / tk_n, tk = r % tk_n; const int idx = tid + 512 * hh, kk = idx >> 4, cc = (idx & 15) * 4, k = tk * 64 + kk, c = tc * 64 + cc;
;                     if (j.in != nullptr && k < j.K && c < j.ncols) { v[u][hh] = *(const f32x4*)(j.in + bi * j.ibs + (size_t)k * j.ld_in + c) * j.mul; if (j.scale) v[u][hh] *= j.scale[k]; } } } }
.LBB0_873:
	v_mov_b32_e32 v64, 0
	v_mov_b32_e32 v65, 0
	v_mov_b32_e32 v66, 0
	v_mov_b32_e32 v67, 0
	v_mov_b32_e32 v68, 0
	v_mov_b32_e32 v69, 0
	v_mov_b32_e32 v70, 0
	v_mov_b32_e32 v71, 0
	v_mov_b32_e32 v72, 0
	v_mov_b32_e32 v73, 0
	v_mov_b32_e32 v74, 0
	v_mov_b32_e32 v75, 0
	v_mov_b32_e32 v76, 0
	v_mov_b32_e32 v77, 0
	v_mov_b32_e32 v78, 0
	v_mov_b32_e32 v79, 0
	v_mov_b32_e32 v80, 0
	v_mov_b32_e32 v81, 0
	v_mov_b32_e32 v82, 0
	v_mov_b32_e32 v83, 0
	v_mov_b32_e32 v84, 0
	v_mov_b32_e32 v85, 0
	v_mov_b32_e32 v86, 0
	v_mov_b32_e32 v87, 0
	v_mov_b32_e32 v88, 0
	v_mov_b32_e32 v89, 0
	v_mov_b32_e32 v90, 0
	v_mov_b32_e32 v91, 0
	v_mov_b32_e32 v92, 0
	v_mov_b32_e32 v93, 0
	v_mov_b32_e32 v94, 0
	v_mov_b32_e32 v95, 0
	v_mov_b32_e32 v96, 1.0
	v_mov_b32_e32 v98, 1.0
	v_mov_b32_e32 v100, 1.0
	v_mov_b32_e32 v102, 1.0
	v_mov_b32_e32 v104, 1.0
	v_mov_b32_e32 v106, 1.0
	v_mov_b32_e32 v108, 1.0
	v_mov_b32_e32 v110, 1.0
	s_abs_i32 s6, s73
	s_mul_hi_u32 s5, s6, s81
	s_mul_i32 s7, s5, s74
	s_ashr_i32 s4, s73, 31
	s_sub_i32 s6, s6, s7
	s_xor_b32 s4, s4, s79
	s_add_i32 s7, s5, 1
	s_sub_i32 s8, s6, s74
	s_cmp_ge_u32 s6, s74
	s_cselect_b32 s9, s7, s5
	s_cselect_b32 s10, s8, s6
	s_add_i32 s11, s9, 1
	s_cmp_ge_u32 s10, s74
	s_cselect_b32 s9, s11, s9
	s_xor_b32 s9, s9, s4
	s_sub_i32 s60, s9, s4
	s_mul_i32 s9, s60, s72
	s_sub_i32 s9, s73, s9
	s_abs_i32 s11, s9
	s_mul_hi_u32 s12, s11, s85
	s_mul_i32 s13, s12, s75
	s_ashr_i32 s10, s9, 31
	s_sub_i32 s11, s11, s13
	s_xor_b32 s10, s10, s84
	s_add_i32 s13, s12, 1
	s_sub_i32 s14, s11, s75
	s_cmp_ge_u32 s11, s75
	s_cselect_b32 s12, s13, s12
	s_cselect_b32 s11, s14, s11
	s_add_i32 s13, s12, 1
	s_cmp_ge_u32 s11, s75
	s_cselect_b32 s11, s13, s12
	s_xor_b32 s11, s11, s10
	s_sub_i32 s10, s11, s10
	s_mul_i32 s11, s10, s70
	s_sub_i32 s9, s9, s11
	s_lshl_b32 s87, s9, 6
	v_add_u32_e32 v8, s87, v39
	s_lshl_b32 s80, s10, 6
	v_or_b32_e32 v10, s80, v38
	v_cmp_gt_i32_e32 vcc, s28, v8
	s_and_b64 s[10:11], s[50:51], vcc
	v_cmp_gt_i32_e64 s[42:43], s65, v10
	s_and_b64 s[10:11], s[10:11], s[42:43]
	v_mov_b32_e32 v2, 0
	v_ashrrev_i32_e32 v11, 31, v10
	v_mov_b32_e32 v6, 0
	v_mov_b32_e32 v7, 0
	v_mov_b32_e32 v4, 0
	v_mov_b32_e32 v5, 0
	s_and_saveexec_b64 s[44:45], s[10:11]
	s_cbranch_execz .LBB0_876
	s_cmp_ge_u32 s6, s74
	s_cselect_b32 s9, s7, s5
	s_cselect_b32 s10, s8, s6
	s_add_i32 s11, s9, 1
	s_cmp_ge_u32 s10, s74
	s_cselect_b32 s9, s11, s9
	s_xor_b32 s9, s9, s4
	s_sub_i32 s9, s9, s4
	s_ashr_i32 s10, s9, 31
	s_mul_i32 s10, s69, s10
	s_mul_hi_u32 s11, s69, s9
	s_add_i32 s10, s11, s10
	s_mul_i32 s11, s64, s9
	s_add_i32 s11, s10, s11
	s_mul_i32 s10, s69, s9
	s_lshl_b64 s[10:11], s[10:11], 2
	s_add_u32 s10, s26, s10
	s_addc_u32 s11, s27, s11
	v_mad_i64_i32 v[4:5], s[12:13], v8, s66, 0
	v_lshl_add_u64 v[4:5], v[4:5], 2, s[10:11]
	v_lshl_add_u64 v[4:5], v[10:11], 2, v[4:5]
	global_load_dwordx4 v[64:67], v[4:5], off
	s_andn2_b64 vcc, exec, s[54:55]
	s_cbranch_vccnz .LBB0_876
	v_ashrrev_i32_e32 v9, 31, v8
	v_lshl_add_u64 v[8:9], v[8:9], 2, s[20:21]
	global_load_dword v96, v[8:9], off
.LBB0_876:
	s_or_b64 exec, exec, s[44:45]
	v_add_u32_e32 v12, s87, v40
	v_cmp_gt_i32_e32 vcc, s28, v12
	s_and_b64 s[10:11], s[50:51], vcc
	s_and_b64 s[10:11], s[10:11], s[42:43]
	v_mov_b32_e32 v3, 0
	v_mov_b32_e32 v8, 0
	v_mov_b32_e32 v9, 0
	s_and_saveexec_b64 s[42:43], s[10:11]
	s_cbranch_execz .LBB0_879
	s_cmp_ge_u32 s6, s74
	s_cselect_b32 s5, s7, s5
	s_cselect_b32 s6, s8, s6
	s_add_i32 s7, s5, 1
	s_cmp_ge_u32 s6, s74
	s_cselect_b32 s5, s7, s5
	s_xor_b32 s5, s5, s4
	s_sub_i32 s4, s5, s4
	s_ashr_i32 s5, s4, 31
	s_mul_i32 s5, s69, s5
	s_mul_hi_u32 s6, s69, s4
	s_add_i32 s5, s6, s5
	s_mul_i32 s6, s64, s4
	s_add_i32 s5, s5, s6
	s_mul_i32 s4, s69, s4
	s_lshl_b64 s[4:5], s[4:5], 2
	s_add_u32 s4, s26, s4
	s_addc_u32 s5, s27, s5
	v_mad_i64_i32 v[2:3], s[6:7], v12, s66, 0
	v_lshl_add_u64 v[2:3], v[2:3], 2, s[4:5]
	v_lshl_add_u64 v[2:3], v[10:11], 2, v[2:3]
	global_load_dwordx4 v[68:71], v[2:3], off
	s_andn2_b64 vcc, exec, s[54:55]
	s_cbranch_vccnz .LBB0_879
	v_ashrrev_i32_e32 v13, 31, v12
	v_lshl_add_u64 v[10:11], v[12:13], 2, s[20:21]
	global_load_dword v98, v[10:11], off
.LBB0_879:
	s_or_b64 exec, exec, s[42:43]
	s_add_i32 s4, s73, s96
	s_cmp_lt_i32 s4, s71
	v_mov_b32_e32 v10, 0
	s_cselect_b64 s[44:45], -1, 0
	s_cmp_ge_i32 s4, s71
	v_mov_b32_e32 v14, 0
	v_mov_b32_e32 v15, 0
	v_mov_b32_e32 v12, 0
	v_mov_b32_e32 v13, 0
	s_cbranch_scc1 .LBB0_884
	s_abs_i32 s7, s4
	s_mul_hi_u32 s5, s7, s81
	s_mul_i32 s8, s5, s74
	s_sub_i32 s7, s7, s8
	s_ashr_i32 s6, s4, 31
	s_sub_i32 s10, s7, s74
	s_cmp_ge_u32 s7, s74
	s_cselect_b64 s[46:47], -1, 0
	s_and_b64 s[8:9], s[46:47], exec
	s_cselect_b32 s7, s10, s7
	s_sub_i32 s10, s7, s74
	s_cmp_ge_u32 s7, s74
	s_cselect_b64 s[48:49], -1, 0
	s_and_b64 s[8:9], s[48:49], exec
	s_cselect_b32 s7, s10, s7
	s_xor_b32 s7, s7, s6
	s_sub_i32 s7, s7, s6
	s_abs_i32 s9, s7
	s_mul_hi_u32 s10, s9, s85
	s_mul_i32 s11, s10, s75
	s_ashr_i32 s8, s7, 31
	s_sub_i32 s9, s9, s11
	s_xor_b32 s8, s8, s84
	s_add_i32 s11, s10, 1
	s_sub_i32 s12, s9, s75
	s_cmp_ge_u32 s9, s75
	s_cselect_b32 s10, s11, s10
	s_cselect_b32 s9, s12, s9
	s_add_i32 s11, s10, 1
	s_cmp_ge_u32 s9, s75
	s_cselect_b32 s9, s11, s10
	s_xor_b32 s9, s9, s8
	s_sub_i32 s8, s9, s8
	s_mul_i32 s9, s8, s70
	s_sub_i32 s7, s7, s9
	v_lshl_add_u32 v16, s7, 6, v39
	v_lshl_or_b32 v18, s8, 6, v38
	v_cmp_gt_i32_e32 vcc, s28, v16
	s_and_b64 s[8:9], s[50:51], vcc
	v_cmp_gt_i32_e32 vcc, s65, v18
	s_and_b64 s[8:9], s[8:9], vcc
	v_mov_b32_e32 v13, 0
	v_mov_b32_e32 v12, 0
	v_mov_b32_e32 v15, 0
	v_mov_b32_e32 v14, 0
	s_and_saveexec_b64 s[42:43], s[8:9]
	s_cbranch_execz .LBB0_883
	s_xor_b32 s8, s6, s79
	s_add_i32 s9, s5, 1
	s_and_b64 s[6:7], s[46:47], exec
	s_cselect_b32 s5, s9, s5
	s_add_i32 s9, s5, 1
	s_and_b64 s[6:7], s[48:49], exec
	s_cselect_b32 s5, s9, s5
	s_xor_b32 s5, s5, s8
	s_sub_i32 s5, s5, s8
	s_ashr_i32 s6, s5, 31
	s_mul_i32 s6, s69, s6
	s_mul_hi_u32 s7, s69, s5
	s_add_i32 s6, s7, s6
	s_mul_i32 s7, s64, s5
	s_add_i32 s7, s6, s7
	s_mul_i32 s6, s69, s5
	s_lshl_b64 s[6:7], s[6:7], 2
	s_add_u32 s6, s26, s6
	s_addc_u32 s7, s27, s7
	v_mad_i64_i32 v[12:13], s[8:9], v16, s66, 0
	v_lshl_add_u64 v[12:13], v[12:13], 2, s[6:7]
	v_ashrrev_i32_e32 v19, 31, v18
	v_lshl_add_u64 v[12:13], v[18:19], 2, v[12:13]
	global_load_dwordx4 v[72:75], v[12:13], off
	s_andn2_b64 vcc, exec, s[54:55]
	s_cbranch_vccnz .LBB0_883
	v_ashrrev_i32_e32 v17, 31, v16
	v_lshl_add_u64 v[16:17], v[16:17], 2, s[20:21]
	global_load_dword v100, v[16:17], off

; __device__ __forceinline__ void run_job(LAS float* tl, const Job j, int& tile_base) {
;     ...
;         for (int u = 0; u < 4; ++u) { const int t = t0 + u * G;
; #pragma unroll
;             for (int hh = 0; hh < 2; ++hh) { v[u][hh] = (f32x4){0.f, 0.f, 0.f, 0.f};
;                 if (t < total) { const int bi = t / per, r = t % per, tc = r / tk_n, tk = r % tk_n; const int idx = tid + 512 * hh, kk = idx >> 4, cc = (idx & 15) * 4, k = tk * 64 + kk, c = tc * 64 + cc;
;                     if (j.in != nullptr && k < j.K && c < j.ncols) { v[u][hh] = *(const f32x4*)(j.in + bi * j.ibs + (size_t)k * j.ld_in + c) * j.mul; if (j.scale) v[u][hh] *= j.scale[k]; } } } }
.LBB0_884:
	v_cndmask_b32_e64 v11, 0, 1, s[44:45]
	v_cmp_ne_u32_e64 s[42:43], 1, v11
	s_andn2_b64 vcc, exec, s[44:45]
	v_mov_b32_e32 v11, 0
	v_mov_b32_e32 v16, 0
	v_mov_b32_e32 v17, 0
	s_cbranch_vccnz .LBB0_889
	s_abs_i32 s7, s4
	s_mul_hi_u32 s5, s7, s81
	s_mul_i32 s8, s5, s74
	s_sub_i32 s7, s7, s8
	s_ashr_i32 s6, s4, 31
	s_sub_i32 s10, s7, s74
	s_cmp_ge_u32 s7, s74
	s_cselect_b64 s[46:47], -1, 0
	s_and_b64 s[8:9], s[46:47], exec
	s_cselect_b32 s7, s10, s7
	s_sub_i32 s10, s7, s74
	s_cmp_ge_u32 s7, s74
	s_cselect_b64 s[48:49], -1, 0
	s_and_b64 s[8:9], s[48:49], exec
	s_cselect_b32 s7, s10, s7
	s_xor_b32 s7, s7, s6
	s_sub_i32 s7, s7, s6
	s_abs_i32 s9, s7
	s_mul_hi_u32 s10, s9, s85
	s_mul_i32 s11, s10, s75
	s_ashr_i32 s8, s7, 31
	s_sub_i32 s9, s9, s11
	s_xor_b32 s8, s8, s84
	s_add_i32 s11, s10, 1
	s_sub_i32 s12, s9, s75
	s_cmp_ge_u32 s9, s75
	s_cselect_b32 s10, s11, s10
	s_cselect_b32 s9, s12, s9
	s_add_i32 s11, s10, 1
	s_cmp_ge_u32 s9, s75
	s_cselect_b32 s9, s11, s10
	s_xor_b32 s9, s9, s8
	s_sub_i32 s8, s9, s8
	s_mul_i32 s9, s8, s70
	s_sub_i32 s7, s7, s9
	v_lshl_add_u32 v18, s7, 6, v40
	v_lshl_or_b32 v20, s8, 6, v38
	v_cmp_gt_i32_e32 vcc, s28, v18
	s_and_b64 s[8:9], s[50:51], vcc
	v_cmp_gt_i32_e32 vcc, s65, v20
	s_and_b64 s[8:9], s[8:9], vcc
	v_mov_b32_e32 v17, 0
	v_mov_b32_e32 v16, 0
	v_mov_b32_e32 v11, 0
	v_mov_b32_e32 v10, 0
	s_and_saveexec_b64 s[44:45], s[8:9]
	s_cbranch_execz .LBB0_888
	s_xor_b32 s8, s6, s79
	s_add_i32 s9, s5, 1
	s_and_b64 s[6:7], s[46:47], exec
	s_cselect_b32 s5, s9, s5
	s_add_i32 s9, s5, 1
	s_and_b64 s[6:7], s[48:49], exec
	s_cselect_b32 s5, s9, s5
	s_xor_b32 s5, s5, s8
	s_sub_i32 s5, s5, s8
	s_ashr_i32 s6, s5, 31
	s_mul_i32 s6, s69, s6
	s_mul_hi_u32 s7, s69, s5
	s_add_i32 s6, s7, s6
	s_mul_i32 s7, s64, s5
	s_add_i32 s7, s6, s7
	s_mul_i32 s6, s69, s5
	s_lshl_b64 s[6:7], s[6:7], 2
	s_add_u32 s6, s26, s6
	s_addc_u32 s7, s27, s7
	v_mad_i64_i32 v[10:11], s[8:9], v18, s66, 0
	v_lshl_add_u64 v[10:11], v[10:11], 2, s[6:7]
	v_ashrrev_i32_e32 v21, 31, v20
	v_lshl_add_u64 v[10:11], v[20:21], 2, v[10:11]
	global_load_dwordx4 v[76:79], v[10:11], off
	s_andn2_b64 vcc, exec, s[54:55]
	s_cbranch_vccnz .LBB0_888
	v_ashrrev_i32_e32 v19, 31, v18
	v_lshl_add_u64 v[18:19], v[18:19], 2, s[20:21]
	global_load_dword v102, v[18:19], off

; __device__ __forceinline__ void run_job(LAS float* tl, const Job j, int& tile_base) {
;     ...
;         for (int u = 0; u < 4; ++u) { const int t = t0 + u * G;
; #pragma unroll
;             for (int hh = 0; hh < 2; ++hh) { v[u][hh] = (f32x4){0.f, 0.f, 0.f, 0.f};
;                 if (t < total) { const int bi = t / per, r = t % per, tc = r / tk_n, tk = r % tk_n; const int idx = tid + 512 * hh, kk = idx >> 4, cc = (idx & 15) * 4, k = tk * 64 + kk, c = tc * 64 + cc;
;                     if (j.in != nullptr && k < j.K && c < j.ncols) { v[u][hh] = *(const f32x4*)(j.in + bi * j.ibs + (size_t)k * j.ld_in + c) * j.mul; if (j.scale) v[u][hh] *= j.scale[k]; } } } }
.LBB0_889:
	s_add_i32 s5, s4, s96
	s_cmp_lt_i32 s5, s71
	v_mov_b32_e32 v18, 0
	s_cselect_b64 s[46:47], -1, 0
	s_cmp_ge_i32 s5, s71
	v_mov_b32_e32 v22, 0
	v_mov_b32_e32 v23, 0
	v_mov_b32_e32 v20, 0
	v_mov_b32_e32 v21, 0
	s_cbranch_scc1 .LBB0_894
	s_abs_i32 s8, s5
	s_mul_hi_u32 s6, s8, s81
	s_mul_i32 s9, s6, s74
	s_sub_i32 s10, s8, s9
	s_ashr_i32 s7, s5, 31
	s_sub_i32 s11, s10, s74
	s_cmp_ge_u32 s10, s74
	s_cselect_b64 s[48:49], -1, 0
	s_and_b64 s[8:9], s[48:49], exec
	s_cselect_b32 s10, s11, s10
	s_sub_i32 s11, s10, s74
	s_cmp_ge_u32 s10, s74
	s_cselect_b64 s[56:57], -1, 0
	s_and_b64 s[8:9], s[56:57], exec
	s_cselect_b32 s8, s11, s10
	s_xor_b32 s8, s8, s7
	s_sub_i32 s8, s8, s7
	s_abs_i32 s10, s8
	s_mul_hi_u32 s11, s10, s85
	s_mul_i32 s12, s11, s75
	s_ashr_i32 s9, s8, 31
	s_sub_i32 s10, s10, s12
	s_xor_b32 s9, s9, s84
	s_add_i32 s12, s11, 1
	s_sub_i32 s13, s10, s75
	s_cmp_ge_u32 s10, s75
	s_cselect_b32 s11, s12, s11
	s_cselect_b32 s10, s13, s10
	s_add_i32 s12, s11, 1
	s_cmp_ge_u32 s10, s75
	s_cselect_b32 s10, s12, s11
	s_xor_b32 s10, s10, s9
	s_sub_i32 s9, s10, s9
	s_mul_i32 s10, s9, s70
	s_sub_i32 s8, s8, s10
	v_lshl_add_u32 v24, s8, 6, v39
	v_lshl_or_b32 v26, s9, 6, v38
	v_cmp_gt_i32_e32 vcc, s28, v24
	s_and_b64 s[8:9], s[50:51], vcc
	v_cmp_gt_i32_e32 vcc, s65, v26
	s_and_b64 s[8:9], s[8:9], vcc
	v_mov_b32_e32 v21, 0
	v_mov_b32_e32 v20, 0
	v_mov_b32_e32 v23, 0
	v_mov_b32_e32 v22, 0
	s_and_saveexec_b64 s[44:45], s[8:9]
	s_cbranch_execz .LBB0_893
	s_xor_b32 s10, s7, s79
	s_add_i32 s7, s6, 1
	s_and_b64 s[8:9], s[48:49], exec
	s_cselect_b32 s8, s7, s6
	s_add_i32 s9, s8, 1
	s_and_b64 s[6:7], s[56:57], exec
	s_cselect_b32 s6, s9, s8
	s_xor_b32 s6, s6, s10
	s_sub_i32 s6, s6, s10
	s_ashr_i32 s7, s6, 31
	s_mul_i32 s7, s69, s7
	s_mul_hi_u32 s8, s69, s6
	s_add_i32 s7, s8, s7
	s_mul_i32 s8, s64, s6
	s_add_i32 s7, s7, s8
	s_mul_i32 s6, s69, s6
	s_lshl_b64 s[6:7], s[6:7], 2
	s_add_u32 s6, s26, s6
	s_addc_u32 s7, s27, s7
	v_mad_i64_i32 v[20:21], s[8:9], v24, s66, 0
	v_lshl_add_u64 v[20:21], v[20:21], 2, s[6:7]
	v_ashrrev_i32_e32 v27, 31, v26
	v_lshl_add_u64 v[20:21], v[26:27], 2, v[20:21]
	global_load_dwordx4 v[80:83], v[20:21], off
	s_andn2_b64 vcc, exec, s[54:55]
	s_cbranch_vccnz .LBB0_893
	v_ashrrev_i32_e32 v25, 31, v24
	v_lshl_add_u64 v[24:25], v[24:25], 2, s[20:21]
	global_load_dword v104, v[24:25], off

; __device__ __forceinline__ void run_job(LAS float* tl, const Job j, int& tile_base) {
;     ...
;         for (int u = 0; u < 4; ++u) { const int t = t0 + u * G;
; #pragma unroll
;             for (int hh = 0; hh < 2; ++hh) { v[u][hh] = (f32x4){0.f, 0.f, 0.f, 0.f};
;                 if (t < total) { const int bi = t / per, r = t % per, tc = r / tk_n, tk = r % tk_n; const int idx = tid + 512 * hh, kk = idx >> 4, cc = (idx & 15) * 4, k = tk * 64 + kk, c = tc * 64 + cc;
;                     if (j.in != nullptr && k < j.K && c < j.ncols) { v[u][hh] = *(const f32x4*)(j.in + bi * j.ibs + (size_t)k * j.ld_in + c) * j.mul; if (j.scale) v[u][hh] *= j.scale[k]; } } } }
.LBB0_894:
	v_cndmask_b32_e64 v19, 0, 1, s[46:47]
	v_cmp_ne_u32_e64 s[44:45], 1, v19
	s_andn2_b64 vcc, exec, s[46:47]
	v_mov_b32_e32 v19, 0
	v_mov_b32_e32 v24, 0
	v_mov_b32_e32 v25, 0
	s_cbranch_vccnz .LBB0_899
	s_abs_i32 s8, s5
	s_mul_hi_u32 s6, s8, s81
	s_mul_i32 s9, s6, s74
	s_sub_i32 s10, s8, s9
	s_ashr_i32 s7, s5, 31
	s_sub_i32 s11, s10, s74
	s_cmp_ge_u32 s10, s74
	s_cselect_b64 s[48:49], -1, 0
	s_and_b64 s[8:9], s[48:49], exec
	s_cselect_b32 s10, s11, s10
	s_sub_i32 s11, s10, s74
	s_cmp_ge_u32 s10, s74
	s_cselect_b64 s[56:57], -1, 0
	s_and_b64 s[8:9], s[56:57], exec
	s_cselect_b32 s8, s11, s10
	s_xor_b32 s8, s8, s7
	s_sub_i32 s8, s8, s7
	s_abs_i32 s10, s8
	s_mul_hi_u32 s11, s10, s85
	s_mul_i32 s12, s11, s75
	s_ashr_i32 s9, s8, 31
	s_sub_i32 s10, s10, s12
	s_xor_b32 s9, s9, s84
	s_add_i32 s12, s11, 1
	s_sub_i32 s13, s10, s75
	s_cmp_ge_u32 s10, s75
	s_cselect_b32 s11, s12, s11
	s_cselect_b32 s10, s13, s10
	s_add_i32 s12, s11, 1
	s_cmp_ge_u32 s10, s75
	s_cselect_b32 s10, s12, s11
	s_xor_b32 s10, s10, s9
	s_sub_i32 s9, s10, s9
	s_mul_i32 s10, s9, s70
	s_sub_i32 s8, s8, s10
	v_lshl_add_u32 v26, s8, 6, v40
	v_lshl_or_b32 v28, s9, 6, v38
	v_cmp_gt_i32_e32 vcc, s28, v26
	s_and_b64 s[8:9], s[50:51], vcc
	v_cmp_gt_i32_e32 vcc, s65, v28
	s_and_b64 s[8:9], s[8:9], vcc
	v_mov_b32_e32 v25, 0
	v_mov_b32_e32 v24, 0
	v_mov_b32_e32 v19, 0
	v_mov_b32_e32 v18, 0
	s_and_saveexec_b64 s[46:47], s[8:9]
	s_cbranch_execz .LBB0_898
	s_xor_b32 s10, s7, s79
	s_add_i32 s7, s6, 1
	s_and_b64 s[8:9], s[48:49], exec
	s_cselect_b32 s8, s7, s6
	s_add_i32 s9, s8, 1
	s_and_b64 s[6:7], s[56:57], exec
	s_cselect_b32 s6, s9, s8
	s_xor_b32 s6, s6, s10
	s_sub_i32 s6, s6, s10
	s_ashr_i32 s7, s6, 31
	s_mul_i32 s7, s69, s7
	s_mul_hi_u32 s8, s69, s6
	s_add_i32 s7, s8, s7
	s_mul_i32 s8, s64, s6
	s_add_i32 s7, s7, s8
	s_mul_i32 s6, s69, s6
	s_lshl_b64 s[6:7], s[6:7], 2
	s_add_u32 s6, s26, s6
	s_addc_u32 s7, s27, s7
	v_mad_i64_i32 v[18:19], s[8:9], v26, s66, 0
	v_lshl_add_u64 v[18:19], v[18:19], 2, s[6:7]
	v_ashrrev_i32_e32 v29, 31, v28
	v_lshl_add_u64 v[18:19], v[28:29], 2, v[18:19]
	global_load_dwordx4 v[84:87], v[18:19], off
	s_andn2_b64 vcc, exec, s[54:55]
	s_cbranch_vccnz .LBB0_898
	v_ashrrev_i32_e32 v27, 31, v26
	v_lshl_add_u64 v[26:27], v[26:27], 2, s[20:21]
	global_load_dword v106, v[26:27], off

; __device__ __forceinline__ void run_job(LAS float* tl, const Job j, int& tile_base) {
;     ...
;         for (int u = 0; u < 4; ++u) { const int t = t0 + u * G;
; #pragma unroll
;             for (int hh = 0; hh < 2; ++hh) { v[u][hh] = (f32x4){0.f, 0.f, 0.f, 0.f};
;                 if (t < total) { const int bi = t / per, r = t % per, tc = r / tk_n, tk = r % tk_n; const int idx = tid + 512 * hh, kk = idx >> 4, cc = (idx & 15) * 4, k = tk * 64 + kk, c = tc * 64 + cc;
;                     if (j.in != nullptr && k < j.K && c < j.ncols) { v[u][hh] = *(const f32x4*)(j.in + bi * j.ibs + (size_t)k * j.ld_in + c) * j.mul; if (j.scale) v[u][hh] *= j.scale[k]; } } } }
.LBB0_899:
	s_add_i32 s6, s5, s96
	s_cmp_lt_i32 s6, s71
	v_mov_b32_e32 v26, 0
	s_cselect_b64 s[48:49], -1, 0
	s_cmp_ge_i32 s6, s71
	v_mov_b32_e32 v30, 0
	v_mov_b32_e32 v31, 0
	v_mov_b32_e32 v28, 0
	v_mov_b32_e32 v29, 0
	s_cbranch_scc1 .LBB0_904
	s_abs_i32 s9, s6
	s_mul_hi_u32 s7, s9, s81
	s_mul_i32 s10, s7, s74
	s_sub_i32 s9, s9, s10
	s_ashr_i32 s8, s6, 31
	s_sub_i32 s12, s9, s74
	s_cmp_ge_u32 s9, s74
	s_cselect_b64 s[56:57], -1, 0
	s_and_b64 s[10:11], s[56:57], exec
	s_cselect_b32 s9, s12, s9
	s_sub_i32 s12, s9, s74
	s_cmp_ge_u32 s9, s74
	s_cselect_b64 s[58:59], -1, 0
	s_and_b64 s[10:11], s[58:59], exec
	s_cselect_b32 s9, s12, s9
	s_xor_b32 s9, s9, s8
	s_sub_i32 s9, s9, s8
	s_abs_i32 s11, s9
	s_mul_hi_u32 s12, s11, s85
	s_mul_i32 s13, s12, s75
	s_ashr_i32 s10, s9, 31
	s_sub_i32 s11, s11, s13
	s_xor_b32 s10, s10, s84
	s_add_i32 s13, s12, 1
	s_sub_i32 s14, s11, s75
	s_cmp_ge_u32 s11, s75
	s_cselect_b32 s12, s13, s12
	s_cselect_b32 s11, s14, s11
	s_add_i32 s13, s12, 1
	s_cmp_ge_u32 s11, s75
	s_cselect_b32 s11, s13, s12
	s_xor_b32 s11, s11, s10
	s_sub_i32 s10, s11, s10
	s_mul_i32 s11, s10, s70
	s_sub_i32 s9, s9, s11
	v_lshl_add_u32 v32, s9, 6, v39
	v_lshl_or_b32 v34, s10, 6, v38
	v_cmp_gt_i32_e32 vcc, s28, v32
	s_and_b64 s[10:11], s[50:51], vcc
	v_cmp_gt_i32_e32 vcc, s65, v34
	s_and_b64 s[10:11], s[10:11], vcc
	v_mov_b32_e32 v29, 0
	v_mov_b32_e32 v28, 0
	v_mov_b32_e32 v31, 0
	v_mov_b32_e32 v30, 0
	s_and_saveexec_b64 s[46:47], s[10:11]
	s_cbranch_execz .LBB0_903
	s_xor_b32 s10, s8, s79
	s_add_i32 s11, s7, 1
	s_and_b64 s[8:9], s[56:57], exec
	s_cselect_b32 s7, s11, s7
	s_add_i32 s11, s7, 1
	s_and_b64 s[8:9], s[58:59], exec
	s_cselect_b32 s7, s11, s7
	s_xor_b32 s7, s7, s10
	s_sub_i32 s7, s7, s10
	s_ashr_i32 s8, s7, 31
	s_mul_i32 s8, s69, s8
	s_mul_hi_u32 s9, s69, s7
	s_add_i32 s8, s9, s8
	s_mul_i32 s9, s64, s7
	s_add_i32 s9, s8, s9
	s_mul_i32 s8, s69, s7
	s_lshl_b64 s[8:9], s[8:9], 2
	s_add_u32 s8, s26, s8
	s_addc_u32 s9, s27, s9
	v_mad_i64_i32 v[28:29], s[10:11], v32, s66, 0
	v_lshl_add_u64 v[28:29], v[28:29], 2, s[8:9]
	v_ashrrev_i32_e32 v35, 31, v34
	v_lshl_add_u64 v[28:29], v[34:35], 2, v[28:29]
	global_load_dwordx4 v[88:91], v[28:29], off
	s_andn2_b64 vcc, exec, s[54:55]
	s_cbranch_vccnz .LBB0_903
	v_ashrrev_i32_e32 v33, 31, v32
	v_lshl_add_u64 v[32:33], v[32:33], 2, s[20:21]
	global_load_dword v108, v[32:33], off

; __device__ __forceinline__ void run_job(LAS float* tl, const Job j, int& tile_base) {
;     ...
;         for (int u = 0; u < 4; ++u) { const int t = t0 + u * G;
; #pragma unroll
;             for (int hh = 0; hh < 2; ++hh) { v[u][hh] = (f32x4){0.f, 0.f, 0.f, 0.f};
;                 if (t < total) { const int bi = t / per, r = t % per, tc = r / tk_n, tk = r % tk_n; const int idx = tid + 512 * hh, kk = idx >> 4, cc = (idx & 15) * 4, k = tk * 64 + kk, c = tc * 64 + cc;
;                     if (j.in != nullptr && k < j.K && c < j.ncols) { v[u][hh] = *(const f32x4*)(j.in + bi * j.ibs + (size_t)k * j.ld_in + c) * j.mul; if (j.scale) v[u][hh] *= j.scale[k]; } } } }
.LBB0_904:
	v_cndmask_b32_e64 v27, 0, 1, s[48:49]
	v_cmp_ne_u32_e64 s[46:47], 1, v27
	s_andn2_b64 vcc, exec, s[48:49]
	v_mov_b32_e32 v27, 0
	v_mov_b32_e32 v32, 0
	v_mov_b32_e32 v33, 0
	s_cbranch_vccnz .LBB0_909
	s_abs_i32 s9, s6
	s_mul_hi_u32 s7, s9, s81
	s_mul_i32 s10, s7, s74
	s_sub_i32 s9, s9, s10
	s_ashr_i32 s8, s6, 31
	s_sub_i32 s12, s9, s74
	s_cmp_ge_u32 s9, s74
	s_cselect_b64 s[56:57], -1, 0
	s_and_b64 s[10:11], s[56:57], exec
	s_cselect_b32 s9, s12, s9
	s_sub_i32 s12, s9, s74
	s_cmp_ge_u32 s9, s74
	s_cselect_b64 s[58:59], -1, 0
	s_and_b64 s[10:11], s[58:59], exec
	s_cselect_b32 s9, s12, s9
	s_xor_b32 s9, s9, s8
	s_sub_i32 s9, s9, s8
	s_abs_i32 s11, s9
	s_mul_hi_u32 s12, s11, s85
	s_mul_i32 s13, s12, s75
	s_ashr_i32 s10, s9, 31
	s_sub_i32 s11, s11, s13
	s_xor_b32 s10, s10, s84
	s_add_i32 s13, s12, 1
	s_sub_i32 s14, s11, s75
	s_cmp_ge_u32 s11, s75
	s_cselect_b32 s12, s13, s12
	s_cselect_b32 s11, s14, s11
	s_add_i32 s13, s12, 1
	s_cmp_ge_u32 s11, s75
	s_cselect_b32 s11, s13, s12
	s_xor_b32 s11, s11, s10
	s_sub_i32 s10, s11, s10
	s_mul_i32 s11, s10, s70
	s_sub_i32 s9, s9, s11
	v_lshl_add_u32 v34, s9, 6, v40
	v_lshl_or_b32 v36, s10, 6, v38
	v_cmp_gt_i32_e32 vcc, s28, v34
	s_and_b64 s[10:11], s[50:51], vcc
	v_cmp_gt_i32_e32 vcc, s65, v36
	s_and_b64 s[10:11], s[10:11], vcc
	v_mov_b32_e32 v33, 0
	v_mov_b32_e32 v32, 0
	v_mov_b32_e32 v27, 0
	v_mov_b32_e32 v26, 0
	s_and_saveexec_b64 s[48:49], s[10:11]
	s_cbranch_execz .LBB0_908
	s_xor_b32 s10, s8, s79
	s_add_i32 s11, s7, 1
	s_and_b64 s[8:9], s[56:57], exec
	s_cselect_b32 s7, s11, s7
	s_add_i32 s11, s7, 1
	s_and_b64 s[8:9], s[58:59], exec
	s_cselect_b32 s7, s11, s7
	s_xor_b32 s7, s7, s10
	s_sub_i32 s7, s7, s10
	s_ashr_i32 s8, s7, 31
	s_mul_i32 s8, s69, s8
	s_mul_hi_u32 s9, s69, s7
	s_add_i32 s8, s9, s8
	s_mul_i32 s9, s64, s7
	s_add_i32 s9, s8, s9
	s_mul_i32 s8, s69, s7
	s_lshl_b64 s[8:9], s[8:9], 2
	s_add_u32 s8, s26, s8
	s_addc_u32 s9, s27, s9
	v_mad_i64_i32 v[26:27], s[10:11], v34, s66, 0
	v_lshl_add_u64 v[26:27], v[26:27], 2, s[8:9]
	v_ashrrev_i32_e32 v37, 31, v36
	v_lshl_add_u64 v[26:27], v[36:37], 2, v[26:27]
	global_load_dwordx4 v[92:95], v[26:27], off
	s_andn2_b64 vcc, exec, s[54:55]
	s_cbranch_vccnz .LBB0_908
	v_ashrrev_i32_e32 v35, 31, v34
	v_lshl_add_u64 v[34:35], v[34:35], 2, s[20:21]
	global_load_dword v110, v[34:35], off

; __device__ __forceinline__ void run_job(LAS float* tl, const Job j, int& tile_base) {
;     ...
;                     if (j.in != nullptr && k < j.K && c < j.ncols) { v[u][hh] = *(const f32x4*)(j.in + bi * j.ibs + (size_t)k * j.ld_in + c) * j.mul; if (j.scale) v[u][hh] *= j.scale[k]; } } } }
.LBB0_909:
	s_waitcnt vmcnt(0)
	v_pk_mul_f32 v[4:5], s[52:53], v[66:67]
	v_pk_mul_f32 v[6:7], s[22:23], v[64:65]
	v_pk_mul_f32 v[8:9], s[52:53], v[70:71]
	v_pk_mul_f32 v[2:3], s[22:23], v[68:69]
	v_pk_mul_f32 v[12:13], s[52:53], v[74:75]
	v_pk_mul_f32 v[14:15], s[22:23], v[72:73]
	v_pk_mul_f32 v[16:17], s[52:53], v[78:79]
	v_pk_mul_f32 v[10:11], s[22:23], v[76:77]
	v_pk_mul_f32 v[20:21], s[52:53], v[82:83]
	v_pk_mul_f32 v[22:23], s[22:23], v[80:81]
	v_pk_mul_f32 v[24:25], s[52:53], v[86:87]
	v_pk_mul_f32 v[18:19], s[22:23], v[84:85]
	v_pk_mul_f32 v[28:29], s[52:53], v[90:91]
	v_pk_mul_f32 v[30:31], s[22:23], v[88:89]
	v_pk_mul_f32 v[32:33], s[52:53], v[94:95]
	v_pk_mul_f32 v[26:27], s[22:23], v[92:93]
	s_andn2_b64 vcc, exec, s[54:55]
	s_cbranch_vccnz .Lcv_p0_ns
	v_pk_mul_f32 v[4:5], v[4:5], v[96:97] op_sel_hi:[1,0]
	v_pk_mul_f32 v[6:7], v[6:7], v[96:97] op_sel_hi:[1,0]
	v_pk_mul_f32 v[8:9], v[8:9], v[98:99] op_sel_hi:[1,0]
	v_pk_mul_f32 v[2:3], v[2:3], v[98:99] op_sel_hi:[1,0]
	v_pk_mul_f32 v[12:13], v[12:13], v[100:101] op_sel_hi:[1,0]
	v_pk_mul_f32 v[14:15], v[14:15], v[100:101] op_sel_hi:[1,0]
	v_pk_mul_f32 v[16:17], v[16:17], v[102:103] op_sel_hi:[1,0]
	v_pk_mul_f32 v[10:11], v[10:11], v[102:103] op_sel_hi:[1,0]
	v_pk_mul_f32 v[20:21], v[20:21], v[104:105] op_sel_hi:[1,0]
	v_pk_mul_f32 v[22:23], v[22:23], v[104:105] op_sel_hi:[1,0]
	v_pk_mul_f32 v[24:25], v[24:25], v[106:107] op_sel_hi:[1,0]
	v_pk_mul_f32 v[18:19], v[18:19], v[106:107] op_sel_hi:[1,0]
	v_pk_mul_f32 v[28:29], v[28:29], v[108:109] op_sel_hi:[1,0]
	v_pk_mul_f32 v[30:31], v[30:31], v[108:109] op_sel_hi:[1,0]
	v_pk_mul_f32 v[32:33], v[32:33], v[110:111] op_sel_hi:[1,0]
	v_pk_mul_f32 v[26:27], v[26:27], v[110:111] op_sel_hi:[1,0]
